# split barrier: prep-only workgroups also skip the closing workgroup barrier, so only wave 0 pays the arrival round trip
# speedup vs baseline: 1.0208x; 1.0077x over previous
.LBB0_805:
	s_or_b64 exec, exec, s[0:1]
	s_mov_b64 s[0:1], 0
	s_waitcnt lgkmcnt(0)
	v_readlane_b32 s16, v250, 0
	v_readlane_b32 s17, v254, 38
	s_nop 3
	s_cmp_lt_u32 s16, 0x80
	s_cbranch_scc1 .Lsb_cb
	s_cmp_lt_u32 s17, 6
	s_cbranch_scc1 .Lsb_cb
	s_cmp_le_u32 s17, 12
	s_cbranch_scc1 .Lsb_nocb

.Lsb_nocb:
.LBB0_806:
	s_and_b64 vcc, exec, s[0:1]
	s_cbranch_vccnz .LBB0_807
	s_getpc_b64 s[98:99]
